# v61 with the merge-phase tail-first stagger keyed on blockIdx bit 3 (half of every XCD) instead of bit 0 (odd XCDs)
# baseline (speedup 1.0000x reference)
; #define GAS __attribute__((address_space(1)))
;     __device__ __forceinline__ GAS unsigned char* wsp() const { return (GAS unsigned char*)rd(18); }
; __global__ void __launch_bounds__(512, 2) mega_fwd(Params p) {
;     ...
;         if (IN(pb + 3)) { pg8::Gemm g{(const GAS bf16*)(F.wsp() + WS_Y), (const GAS bf16*)(F.wsp() + WS_WBR) + (size_t)l * 3 * D * D, (size_t)MTOT * 1024, (size_t)D * D, MTOT / 256, D / 256, 3, D, MERGE_TAIL, WGM_SQ};
;             pg8::Order S; S.init(g, F.G, (int)blockIdx.x);
;             pg8::EpiMerge E{F.wsp()};
;             pg8::gemm_phase(F.lds, g, S, E, F.wave);
;             { __syncthreads(); pg8::EpiMergeSlab E2{F.wsp()}; pg8::gemm_phase<pg8::EpiMergeSlab, 1>(F.lds, g, S, E2, F.wave); }
.LBB0_934:
	v_readlane_b32 s12, v240, 8
	s_add_u32 s14, s8, 0x28f00000
	v_readlane_b32 s13, v240, 9
	s_mul_i32 s20, s12, 0x300000
	s_addc_u32 s15, s9, 0
	s_lshl_b64 s[12:13], s[20:21], 1
	s_add_u32 s12, s8, s12
	s_addc_u32 s13, s9, s13
	s_add_u32 s20, s12, 0x3600000
	s_addc_u32 s68, s13, 0
	s_cmp_lg_u32 s100, 0
	s_cbranch_scc1 .Lmr_a
	s_bitcmp1_b32 s101, 3
	s_cbranch_scc0 .Lmr_a
	s_mov_b32 s100, 1
	s_branch .LBB0_1062
